# queue peek: when the 8-counter peek shows every queue of the mixer exhausted, thread 0 broadcasts -1 and all waves leave the steal loop at once (skips 6 poll rounds of 2 barriers each); stacked on v21
# speedup vs baseline: 1.0020x; 1.0013x over previous
.Lpk_use_0:
	s_cmp_eq_u32 s16, 0
	s_cbranch_scc1 .Lpk_atom_0
	s_bitcmp1_b32 s98, s0
	s_cbranch_scc0 .Lpk_atom_0
	v_mov_b32_e32 v2, 0x80
	s_and_b32 s99, s98, 0xff
	s_cmp_eq_u32 s99, 0xff
	s_cbranch_scc0 .LBB0_235
	v_mov_b32_e32 v2, -1
	s_branch .LBB0_235

.LBB0_236:
	s_or_b64 exec, exec, s[4:5]
	v_mov_b32_e32 v0, s31
	s_waitcnt lgkmcnt(0)
	s_barrier
	ds_read_b32 v0, v0
	s_waitcnt lgkmcnt(0)
	v_readfirstlane_b32 s1, v0
	s_cmp_eq_u32 s1, -1
	s_cbranch_scc0 .Lpk_rd_0
	s_mov_b32 s16, 7
.Lpk_rd_0:
	s_cmpk_gt_u32 s1, 0x7f
	s_cbranch_scc1 .LBB0_231
	s_and_b32 s2, s18, 7
	s_lshl_b32 s19, s2, 13
	s_mul_i32 s85, s2, 0x1600000
	s_lshl_b32 s86, s0, 4
	s_lshl_b32 s87, s0, 12
	s_mul_i32 s2, s0, 0x1600000
	s_add_u32 s22, s80, s2
	s_addc_u32 s26, s81, 0
	s_lshl_b32 s0, s0, 13
	s_add_u32 s3, s82, s0
	s_addc_u32 s0, s83, 0
	s_branch .LBB0_239

.Lpk_use_1:
	s_cmp_eq_u32 s0, 0
	s_cbranch_scc1 .Lpk_atom_1
	s_bitcmp1_b32 s98, s2
	s_cbranch_scc0 .Lpk_atom_1
	v_mov_b32_e32 v2, 0x80
	s_and_b32 s99, s98, 0xff
	s_cmp_eq_u32 s99, 0xff
	s_cbranch_scc0 .LBB0_316
	v_mov_b32_e32 v2, -1
	s_branch .LBB0_316

.LBB0_317:
	s_or_b64 exec, exec, s[6:7]
	v_mov_b32_e32 v0, s31
	s_waitcnt lgkmcnt(0)
	s_barrier
	ds_read_b32 v0, v0
	s_waitcnt lgkmcnt(0)
	v_readfirstlane_b32 s13, v0
	s_cmp_eq_u32 s13, -1
	s_cbranch_scc0 .Lpk_rd_1
	s_mov_b32 s0, 7
.Lpk_rd_1:
	s_cmpk_gt_u32 s13, 0x7f
	s_cbranch_scc1 .LBB0_312
	s_and_b32 s6, s1, 7
	s_lshl_b32 s3, s6, 12
	s_lshl_b32 s20, s6, 13
	s_lshl_b32 s26, s2, 4
	s_lshl_b32 s70, s2, 12
	s_mul_i32 s2, s2, 0x1600000
	s_add_u32 s71, s80, s2
	s_mul_i32 s22, s6, 0x1600000
	s_addc_u32 s75, s81, 0
	s_branch .LBB0_320

.Lpk_use_2:
	s_cmp_eq_u32 s3, 0
	s_cbranch_scc1 .Lpk_atom_2
	s_bitcmp1_b32 s98, s2
	s_cbranch_scc0 .Lpk_atom_2
	v_mov_b32_e32 v2, 0x80
	s_and_b32 s99, s98, 0xff
	s_cmp_eq_u32 s99, 0xff
	s_cbranch_scc0 .LBB0_395
	v_mov_b32_e32 v2, -1
	s_branch .LBB0_395

.LBB0_396:
	s_or_b64 exec, exec, s[4:5]
	v_mov_b32_e32 v0, s31
	s_waitcnt lgkmcnt(0)
	s_barrier
	ds_read_b32 v0, v0
	s_waitcnt lgkmcnt(0)
	v_readfirstlane_b32 s20, v0
	s_cmp_eq_u32 s20, -1
	s_cbranch_scc0 .Lpk_rd_2
	s_mov_b32 s3, 7
.Lpk_rd_2:
	s_cmpk_gt_u32 s20, 0x7f
	s_cbranch_scc1 .LBB0_391
	s_lshl_b32 s12, s2, 12
	s_mul_i32 s2, s2, 0x1600000
	s_add_u32 s13, s80, s2
	s_addc_u32 s14, s81, 0
	s_branch .LBB0_399
